# seams 2-8: XCC leader now completes its L2 invalidate after the writeback before signalling release (closes a stale-line window); otherwise as v24
# speedup vs baseline: 1.0102x; 1.0001x over previous
; __device__ __forceinline__ unsigned xb_ld(unsigned* p)              { return __hip_atomic_load(p, __ATOMIC_RELAXED, __HIP_MEMORY_SCOPE_AGENT); }
; __device__ __forceinline__ unsigned xb_add(unsigned* p, unsigned v) { return __hip_atomic_fetch_add(p, v, __ATOMIC_RELAXED, __HIP_MEMORY_SCOPE_AGENT); }
; #define XB_SPIN(cond, bar) do { unsigned _sp = 0; while (cond) { __builtin_amdgcn_s_sleep(1); \
;     if ((++_sp & 255u) == 0u) { if (xb_ld(&(bar)[XB_TMO])) break; if (_sp > XB_SPIN_CAP) { atomicAdd(&(bar)[XB_TMO], 1u); break; } } } } while (0)
; __device__ __forceinline__ void xcd_barrier(const XcdBarrier& b) {
;     asm volatile("s_waitcnt vmcnt(0)" ::: "memory");
;     __syncthreads();
;     if (threadIdx.x == 0) {
;         unsigned* bar = b.bar;
;         __builtin_amdgcn_s_waitcnt(0);
;         unsigned nloc = b.st[0], nx = b.st[1];
;         if (nloc == 0u) { xcd_barrier_complete(bar, b.x, nloc, nx); b.st[0] = nloc; b.st[1] = nx; }
;         const unsigned old = xb_add(&bar[XB_XSUB(b.x)], 1u);
;         const unsigned gen = old / nloc;
;         if (old + 1u == (gen + 1u) * nloc) {
;             __builtin_amdgcn_fence(__ATOMIC_RELEASE, "agent");
;             asm volatile("s_waitcnt vmcnt(0)" ::: "memory");
;             const unsigned og = xb_add(&bar[XB_TOP], 1u);
;             const unsigned tg = og / nx;
;             if (og + 1u == (tg + 1u) * nx) xb_add(&bar[XB_TOPGEN], 1u);
;             else XB_SPIN(xb_ld(&bar[XB_TOPGEN]) == tg, bar);
;             __builtin_amdgcn_fence(__ATOMIC_ACQUIRE, "agent");
;             xb_add(&bar[XB_XGEN(b.x)], 1u);
;             asm volatile("s_waitcnt vmcnt(0)" ::: "memory");
.LBB0_175:
	s_waitcnt vmcnt(0) lgkmcnt(0)
	s_barrier
	v_readlane_b32 s74, v252, 15
	v_readlane_b32 s75, v252, 16
	v_readfirstlane_b32 s98, v222
	s_nop 3
	s_cmp_lg_u32 s98, 0
	s_cbranch_scc1 .Lsm2_done
	v_mov_b32_e32 v0, 0x23fc0
	ds_read_b64 v[2:3], v0
	v_readlane_b32 s99, v252, 3
	s_add_u32 s100, s58, 0x507000
	s_addc_u32 s101, s59, 0
	s_lshl_b32 s99, s99, 8
	v_mov_b32_e32 v0, s99
	v_mov_b32_e32 v1, 1
	s_mov_b64 exec, 1
	s_nop 1
	global_atomic_add v4, v0, v1, s[100:101] sc0
	s_waitcnt vmcnt(0) lgkmcnt(0)
	v_readfirstlane_b32 s99, v4
	v_readfirstlane_b32 vcc_lo, v2
	v_readfirstlane_b32 vcc_hi, v3
	s_add_u32 s100, s58, 0x500080
	s_addc_u32 s101, s59, 0
	v_mov_b32_e32 v0, 0
	s_add_u32 s99, s99, 1
	s_mul_i32 s98, vcc_lo, 1
	s_cmp_lg_u32 s99, s98
	s_cbranch_scc1 .Lsm2_nl
	buffer_wbl2 sc1
	s_waitcnt vmcnt(0)
	buffer_inv sc1
	s_waitcnt vmcnt(0)
	global_atomic_add v0, v1, s[100:101]
	s_branch .Lsm2_ld

; __device__ __forceinline__ unsigned xb_ld(unsigned* p)              { return __hip_atomic_load(p, __ATOMIC_RELAXED, __HIP_MEMORY_SCOPE_AGENT); }
; __device__ __forceinline__ unsigned xb_add(unsigned* p, unsigned v) { return __hip_atomic_fetch_add(p, v, __ATOMIC_RELAXED, __HIP_MEMORY_SCOPE_AGENT); }
; #define XB_SPIN(cond, bar) do { unsigned _sp = 0; while (cond) { __builtin_amdgcn_s_sleep(1); \
;     if ((++_sp & 255u) == 0u) { if (xb_ld(&(bar)[XB_TMO])) break; if (_sp > XB_SPIN_CAP) { atomicAdd(&(bar)[XB_TMO], 1u); break; } } } } while (0)
; __device__ __forceinline__ void xcd_barrier(const XcdBarrier& b) {
;     ...
;             const unsigned og = xb_add(&bar[XB_TOP], 1u);
;             const unsigned tg = og / nx;
;             if (og + 1u == (tg + 1u) * nx) xb_add(&bar[XB_TOPGEN], 1u);
;             else XB_SPIN(xb_ld(&bar[XB_TOPGEN]) == tg, bar);
.Lsm2_ld:
	s_mul_i32 s98, vcc_hi, 1
	s_mov_b32 s99, 0

; __device__ __forceinline__ unsigned xb_ld(unsigned* p)              { return __hip_atomic_load(p, __ATOMIC_RELAXED, __HIP_MEMORY_SCOPE_AGENT); }
; __device__ __forceinline__ unsigned xb_add(unsigned* p, unsigned v) { return __hip_atomic_fetch_add(p, v, __ATOMIC_RELAXED, __HIP_MEMORY_SCOPE_AGENT); }
; #define XB_SPIN(cond, bar) do { unsigned _sp = 0; while (cond) { __builtin_amdgcn_s_sleep(1); \
;     if ((++_sp & 255u) == 0u) { if (xb_ld(&(bar)[XB_TMO])) break; if (_sp > XB_SPIN_CAP) { atomicAdd(&(bar)[XB_TMO], 1u); break; } } } } while (0)
; __device__ __forceinline__ void xcd_barrier(const XcdBarrier& b) {
;     asm volatile("s_waitcnt vmcnt(0)" ::: "memory");
;     __syncthreads();
;     if (threadIdx.x == 0) {
;         unsigned* bar = b.bar;
;         __builtin_amdgcn_s_waitcnt(0);
;         unsigned nloc = b.st[0], nx = b.st[1];
;         if (nloc == 0u) { xcd_barrier_complete(bar, b.x, nloc, nx); b.st[0] = nloc; b.st[1] = nx; }
;         const unsigned old = xb_add(&bar[XB_XSUB(b.x)], 1u);
;         const unsigned gen = old / nloc;
;         if (old + 1u == (gen + 1u) * nloc) {
;             __builtin_amdgcn_fence(__ATOMIC_RELEASE, "agent");
;             asm volatile("s_waitcnt vmcnt(0)" ::: "memory");
;             const unsigned og = xb_add(&bar[XB_TOP], 1u);
;             const unsigned tg = og / nx;
;             if (og + 1u == (tg + 1u) * nx) xb_add(&bar[XB_TOPGEN], 1u);
;             else XB_SPIN(xb_ld(&bar[XB_TOPGEN]) == tg, bar);
;             __builtin_amdgcn_fence(__ATOMIC_ACQUIRE, "agent");
;             xb_add(&bar[XB_XGEN(b.x)], 1u);
;             asm volatile("s_waitcnt vmcnt(0)" ::: "memory");
.LBB0_335:
	s_waitcnt vmcnt(0) lgkmcnt(0)
	s_barrier
	v_readfirstlane_b32 s98, v222
	s_nop 3
	s_cmp_lg_u32 s98, 0
	s_cbranch_scc1 .Lsm3_done
	v_mov_b32_e32 v0, 0x23fc0
	ds_read_b64 v[2:3], v0
	v_readlane_b32 s99, v252, 3
	s_add_u32 s100, s58, 0x507000
	s_addc_u32 s101, s59, 0
	s_lshl_b32 s99, s99, 8
	v_mov_b32_e32 v0, s99
	v_mov_b32_e32 v1, 1
	s_mov_b64 exec, 1
	s_nop 1
	global_atomic_add v4, v0, v1, s[100:101] sc0
	s_waitcnt vmcnt(0) lgkmcnt(0)
	v_readfirstlane_b32 s99, v4
	v_readfirstlane_b32 vcc_lo, v2
	v_readfirstlane_b32 vcc_hi, v3
	s_add_u32 s100, s58, 0x500080
	s_addc_u32 s101, s59, 0
	v_mov_b32_e32 v0, 0
	s_add_u32 s99, s99, 1
	s_mul_i32 s98, vcc_lo, 2
	s_cmp_lg_u32 s99, s98
	s_cbranch_scc1 .Lsm3_nl
	buffer_wbl2 sc1
	s_waitcnt vmcnt(0)
	buffer_inv sc1
	s_waitcnt vmcnt(0)
	global_atomic_add v0, v1, s[100:101]
	s_branch .Lsm3_ld

; __device__ __forceinline__ unsigned xb_ld(unsigned* p)              { return __hip_atomic_load(p, __ATOMIC_RELAXED, __HIP_MEMORY_SCOPE_AGENT); }
; __device__ __forceinline__ unsigned xb_add(unsigned* p, unsigned v) { return __hip_atomic_fetch_add(p, v, __ATOMIC_RELAXED, __HIP_MEMORY_SCOPE_AGENT); }
; #define XB_SPIN(cond, bar) do { unsigned _sp = 0; while (cond) { __builtin_amdgcn_s_sleep(1); \
;     if ((++_sp & 255u) == 0u) { if (xb_ld(&(bar)[XB_TMO])) break; if (_sp > XB_SPIN_CAP) { atomicAdd(&(bar)[XB_TMO], 1u); break; } } } } while (0)
; __device__ __forceinline__ void xcd_barrier(const XcdBarrier& b) {
;     ...
;             const unsigned og = xb_add(&bar[XB_TOP], 1u);
;             const unsigned tg = og / nx;
;             if (og + 1u == (tg + 1u) * nx) xb_add(&bar[XB_TOPGEN], 1u);
;             else XB_SPIN(xb_ld(&bar[XB_TOPGEN]) == tg, bar);
.Lsm3_ld:
	s_mul_i32 s98, vcc_hi, 2
	s_mov_b32 s99, 0

; __device__ __forceinline__ unsigned xb_ld(unsigned* p)              { return __hip_atomic_load(p, __ATOMIC_RELAXED, __HIP_MEMORY_SCOPE_AGENT); }
; __device__ __forceinline__ unsigned xb_add(unsigned* p, unsigned v) { return __hip_atomic_fetch_add(p, v, __ATOMIC_RELAXED, __HIP_MEMORY_SCOPE_AGENT); }
; #define XB_SPIN(cond, bar) do { unsigned _sp = 0; while (cond) { __builtin_amdgcn_s_sleep(1); \
;     if ((++_sp & 255u) == 0u) { if (xb_ld(&(bar)[XB_TMO])) break; if (_sp > XB_SPIN_CAP) { atomicAdd(&(bar)[XB_TMO], 1u); break; } } } } while (0)
; __device__ __forceinline__ void xcd_barrier(const XcdBarrier& b) {
;     asm volatile("s_waitcnt vmcnt(0)" ::: "memory");
;     __syncthreads();
;     if (threadIdx.x == 0) {
;         unsigned* bar = b.bar;
;         __builtin_amdgcn_s_waitcnt(0);
;         unsigned nloc = b.st[0], nx = b.st[1];
;         if (nloc == 0u) { xcd_barrier_complete(bar, b.x, nloc, nx); b.st[0] = nloc; b.st[1] = nx; }
;         const unsigned old = xb_add(&bar[XB_XSUB(b.x)], 1u);
;         const unsigned gen = old / nloc;
;         if (old + 1u == (gen + 1u) * nloc) {
;             __builtin_amdgcn_fence(__ATOMIC_RELEASE, "agent");
;             asm volatile("s_waitcnt vmcnt(0)" ::: "memory");
;             const unsigned og = xb_add(&bar[XB_TOP], 1u);
;             const unsigned tg = og / nx;
;             if (og + 1u == (tg + 1u) * nx) xb_add(&bar[XB_TOPGEN], 1u);
;             else XB_SPIN(xb_ld(&bar[XB_TOPGEN]) == tg, bar);
;             __builtin_amdgcn_fence(__ATOMIC_ACQUIRE, "agent");
;             xb_add(&bar[XB_XGEN(b.x)], 1u);
;             asm volatile("s_waitcnt vmcnt(0)" ::: "memory");
.LBB0_500:
	s_waitcnt vmcnt(0) lgkmcnt(0)
	s_barrier
	v_readfirstlane_b32 s98, v222
	s_nop 3
	s_cmp_lg_u32 s98, 0
	s_cbranch_scc1 .Lsm4_done
	v_mov_b32_e32 v0, 0x23fc0
	ds_read_b64 v[2:3], v0
	v_readlane_b32 s99, v252, 3
	s_add_u32 s100, s58, 0x507000
	s_addc_u32 s101, s59, 0
	s_lshl_b32 s99, s99, 8
	v_mov_b32_e32 v0, s99
	v_mov_b32_e32 v1, 1
	s_mov_b64 exec, 1
	s_nop 1
	global_atomic_add v4, v0, v1, s[100:101] sc0
	s_waitcnt vmcnt(0) lgkmcnt(0)
	v_readfirstlane_b32 s99, v4
	v_readfirstlane_b32 vcc_lo, v2
	v_readfirstlane_b32 vcc_hi, v3
	s_add_u32 s100, s58, 0x500080
	s_addc_u32 s101, s59, 0
	v_mov_b32_e32 v0, 0
	s_add_u32 s99, s99, 1
	s_mul_i32 s98, vcc_lo, 3
	s_cmp_lg_u32 s99, s98
	s_cbranch_scc1 .Lsm4_nl
	buffer_wbl2 sc1
	s_waitcnt vmcnt(0)
	buffer_inv sc1
	s_waitcnt vmcnt(0)
	global_atomic_add v0, v1, s[100:101]
	s_branch .Lsm4_ld

; __device__ __forceinline__ unsigned xb_ld(unsigned* p)              { return __hip_atomic_load(p, __ATOMIC_RELAXED, __HIP_MEMORY_SCOPE_AGENT); }
; __device__ __forceinline__ unsigned xb_add(unsigned* p, unsigned v) { return __hip_atomic_fetch_add(p, v, __ATOMIC_RELAXED, __HIP_MEMORY_SCOPE_AGENT); }
; #define XB_SPIN(cond, bar) do { unsigned _sp = 0; while (cond) { __builtin_amdgcn_s_sleep(1); \
;     if ((++_sp & 255u) == 0u) { if (xb_ld(&(bar)[XB_TMO])) break; if (_sp > XB_SPIN_CAP) { atomicAdd(&(bar)[XB_TMO], 1u); break; } } } } while (0)
; __device__ __forceinline__ void xcd_barrier(const XcdBarrier& b) {
;     ...
;             const unsigned og = xb_add(&bar[XB_TOP], 1u);
;             const unsigned tg = og / nx;
;             if (og + 1u == (tg + 1u) * nx) xb_add(&bar[XB_TOPGEN], 1u);
;             else XB_SPIN(xb_ld(&bar[XB_TOPGEN]) == tg, bar);
.Lsm4_ld:
	s_mul_i32 s98, vcc_hi, 3
	s_mov_b32 s99, 0

; __device__ __forceinline__ unsigned xb_ld(unsigned* p)              { return __hip_atomic_load(p, __ATOMIC_RELAXED, __HIP_MEMORY_SCOPE_AGENT); }
; __device__ __forceinline__ unsigned xb_add(unsigned* p, unsigned v) { return __hip_atomic_fetch_add(p, v, __ATOMIC_RELAXED, __HIP_MEMORY_SCOPE_AGENT); }
; #define XB_SPIN(cond, bar) do { unsigned _sp = 0; while (cond) { __builtin_amdgcn_s_sleep(1); \
;     if ((++_sp & 255u) == 0u) { if (xb_ld(&(bar)[XB_TMO])) break; if (_sp > XB_SPIN_CAP) { atomicAdd(&(bar)[XB_TMO], 1u); break; } } } } while (0)
; __device__ __forceinline__ void xcd_barrier(const XcdBarrier& b) {
;     asm volatile("s_waitcnt vmcnt(0)" ::: "memory");
;     __syncthreads();
;     if (threadIdx.x == 0) {
;         unsigned* bar = b.bar;
;         __builtin_amdgcn_s_waitcnt(0);
;         unsigned nloc = b.st[0], nx = b.st[1];
;         if (nloc == 0u) { xcd_barrier_complete(bar, b.x, nloc, nx); b.st[0] = nloc; b.st[1] = nx; }
;         const unsigned old = xb_add(&bar[XB_XSUB(b.x)], 1u);
;         const unsigned gen = old / nloc;
;         if (old + 1u == (gen + 1u) * nloc) {
;             __builtin_amdgcn_fence(__ATOMIC_RELEASE, "agent");
;             asm volatile("s_waitcnt vmcnt(0)" ::: "memory");
;             const unsigned og = xb_add(&bar[XB_TOP], 1u);
;             const unsigned tg = og / nx;
;             if (og + 1u == (tg + 1u) * nx) xb_add(&bar[XB_TOPGEN], 1u);
;             else XB_SPIN(xb_ld(&bar[XB_TOPGEN]) == tg, bar);
;             __builtin_amdgcn_fence(__ATOMIC_ACQUIRE, "agent");
;             xb_add(&bar[XB_XGEN(b.x)], 1u);
;             asm volatile("s_waitcnt vmcnt(0)" ::: "memory");
.LBB0_715:
	s_waitcnt vmcnt(0) lgkmcnt(0)
	s_barrier
	v_readfirstlane_b32 s98, v222
	s_nop 3
	s_cmp_lg_u32 s98, 0
	s_cbranch_scc1 .Lsm5_done
	v_mov_b32_e32 v0, 0x23fc0
	ds_read_b64 v[2:3], v0
	v_readlane_b32 s99, v252, 3
	s_add_u32 s100, s58, 0x507000
	s_addc_u32 s101, s59, 0
	s_lshl_b32 s99, s99, 8
	v_mov_b32_e32 v0, s99
	v_mov_b32_e32 v1, 1
	s_mov_b64 exec, 1
	s_nop 1
	global_atomic_add v4, v0, v1, s[100:101] sc0
	s_waitcnt vmcnt(0) lgkmcnt(0)
	v_readfirstlane_b32 s99, v4
	v_readfirstlane_b32 vcc_lo, v2
	v_readfirstlane_b32 vcc_hi, v3
	s_add_u32 s100, s58, 0x500080
	s_addc_u32 s101, s59, 0
	v_mov_b32_e32 v0, 0
	s_add_u32 s99, s99, 1
	s_mul_i32 s98, vcc_lo, 4
	s_cmp_lg_u32 s99, s98
	s_cbranch_scc1 .Lsm5_nl
	buffer_wbl2 sc1
	s_waitcnt vmcnt(0)
	buffer_inv sc1
	s_waitcnt vmcnt(0)
	global_atomic_add v0, v1, s[100:101]
	s_branch .Lsm5_ld

; __device__ __forceinline__ unsigned xb_ld(unsigned* p)              { return __hip_atomic_load(p, __ATOMIC_RELAXED, __HIP_MEMORY_SCOPE_AGENT); }
; __device__ __forceinline__ unsigned xb_add(unsigned* p, unsigned v) { return __hip_atomic_fetch_add(p, v, __ATOMIC_RELAXED, __HIP_MEMORY_SCOPE_AGENT); }
; #define XB_SPIN(cond, bar) do { unsigned _sp = 0; while (cond) { __builtin_amdgcn_s_sleep(1); \
;     if ((++_sp & 255u) == 0u) { if (xb_ld(&(bar)[XB_TMO])) break; if (_sp > XB_SPIN_CAP) { atomicAdd(&(bar)[XB_TMO], 1u); break; } } } } while (0)
; __device__ __forceinline__ void xcd_barrier(const XcdBarrier& b) {
;     ...
;             const unsigned og = xb_add(&bar[XB_TOP], 1u);
;             const unsigned tg = og / nx;
;             if (og + 1u == (tg + 1u) * nx) xb_add(&bar[XB_TOPGEN], 1u);
;             else XB_SPIN(xb_ld(&bar[XB_TOPGEN]) == tg, bar);
.Lsm5_ld:
	s_mul_i32 s98, vcc_hi, 4
	s_mov_b32 s99, 0

; __device__ __forceinline__ unsigned xb_ld(unsigned* p)              { return __hip_atomic_load(p, __ATOMIC_RELAXED, __HIP_MEMORY_SCOPE_AGENT); }
; __device__ __forceinline__ unsigned xb_add(unsigned* p, unsigned v) { return __hip_atomic_fetch_add(p, v, __ATOMIC_RELAXED, __HIP_MEMORY_SCOPE_AGENT); }
; #define XB_SPIN(cond, bar) do { unsigned _sp = 0; while (cond) { __builtin_amdgcn_s_sleep(1); \
;     if ((++_sp & 255u) == 0u) { if (xb_ld(&(bar)[XB_TMO])) break; if (_sp > XB_SPIN_CAP) { atomicAdd(&(bar)[XB_TMO], 1u); break; } } } } while (0)
; __device__ __forceinline__ void xcd_barrier(const XcdBarrier& b) {
;     asm volatile("s_waitcnt vmcnt(0)" ::: "memory");
;     __syncthreads();
;     if (threadIdx.x == 0) {
;         unsigned* bar = b.bar;
;         __builtin_amdgcn_s_waitcnt(0);
;         unsigned nloc = b.st[0], nx = b.st[1];
;         if (nloc == 0u) { xcd_barrier_complete(bar, b.x, nloc, nx); b.st[0] = nloc; b.st[1] = nx; }
;         const unsigned old = xb_add(&bar[XB_XSUB(b.x)], 1u);
;         const unsigned gen = old / nloc;
;         if (old + 1u == (gen + 1u) * nloc) {
;             __builtin_amdgcn_fence(__ATOMIC_RELEASE, "agent");
;             asm volatile("s_waitcnt vmcnt(0)" ::: "memory");
;             const unsigned og = xb_add(&bar[XB_TOP], 1u);
;             const unsigned tg = og / nx;
;             if (og + 1u == (tg + 1u) * nx) xb_add(&bar[XB_TOPGEN], 1u);
;             else XB_SPIN(xb_ld(&bar[XB_TOPGEN]) == tg, bar);
;             __builtin_amdgcn_fence(__ATOMIC_ACQUIRE, "agent");
;             xb_add(&bar[XB_XGEN(b.x)], 1u);
;             asm volatile("s_waitcnt vmcnt(0)" ::: "memory");
.LBB0_808:
	s_waitcnt vmcnt(0) lgkmcnt(0)
	s_barrier
	v_readfirstlane_b32 s98, v222
	s_nop 3
	s_cmp_lg_u32 s98, 0
	s_cbranch_scc1 .Lsm6_done
	v_mov_b32_e32 v0, 0x23fc0
	ds_read_b64 v[2:3], v0
	v_readlane_b32 s99, v252, 3
	s_add_u32 s100, s58, 0x507000
	s_addc_u32 s101, s59, 0
	s_lshl_b32 s99, s99, 8
	v_mov_b32_e32 v0, s99
	v_mov_b32_e32 v1, 1
	s_mov_b64 exec, 1
	s_nop 1
	global_atomic_add v4, v0, v1, s[100:101] sc0
	s_waitcnt vmcnt(0) lgkmcnt(0)
	v_readfirstlane_b32 s99, v4
	v_readfirstlane_b32 vcc_lo, v2
	v_readfirstlane_b32 vcc_hi, v3
	s_add_u32 s100, s58, 0x500080
	s_addc_u32 s101, s59, 0
	v_mov_b32_e32 v0, 0
	s_add_u32 s99, s99, 1
	s_mul_i32 s98, vcc_lo, 5
	s_cmp_lg_u32 s99, s98
	s_cbranch_scc1 .Lsm6_nl
	buffer_wbl2 sc1
	s_waitcnt vmcnt(0)
	buffer_inv sc1
	s_waitcnt vmcnt(0)
	global_atomic_add v0, v1, s[100:101]
	s_branch .Lsm6_ld

; __device__ __forceinline__ unsigned xb_ld(unsigned* p)              { return __hip_atomic_load(p, __ATOMIC_RELAXED, __HIP_MEMORY_SCOPE_AGENT); }
; __device__ __forceinline__ unsigned xb_add(unsigned* p, unsigned v) { return __hip_atomic_fetch_add(p, v, __ATOMIC_RELAXED, __HIP_MEMORY_SCOPE_AGENT); }
; #define XB_SPIN(cond, bar) do { unsigned _sp = 0; while (cond) { __builtin_amdgcn_s_sleep(1); \
;     if ((++_sp & 255u) == 0u) { if (xb_ld(&(bar)[XB_TMO])) break; if (_sp > XB_SPIN_CAP) { atomicAdd(&(bar)[XB_TMO], 1u); break; } } } } while (0)
; __device__ __forceinline__ void xcd_barrier(const XcdBarrier& b) {
;     ...
;             const unsigned og = xb_add(&bar[XB_TOP], 1u);
;             const unsigned tg = og / nx;
;             if (og + 1u == (tg + 1u) * nx) xb_add(&bar[XB_TOPGEN], 1u);
;             else XB_SPIN(xb_ld(&bar[XB_TOPGEN]) == tg, bar);
.Lsm6_ld:
	s_mul_i32 s98, vcc_hi, 5
	s_mov_b32 s99, 0

; __device__ __forceinline__ unsigned xb_ld(unsigned* p)              { return __hip_atomic_load(p, __ATOMIC_RELAXED, __HIP_MEMORY_SCOPE_AGENT); }
; __device__ __forceinline__ unsigned xb_add(unsigned* p, unsigned v) { return __hip_atomic_fetch_add(p, v, __ATOMIC_RELAXED, __HIP_MEMORY_SCOPE_AGENT); }
; #define XB_SPIN(cond, bar) do { unsigned _sp = 0; while (cond) { __builtin_amdgcn_s_sleep(1); \
;     if ((++_sp & 255u) == 0u) { if (xb_ld(&(bar)[XB_TMO])) break; if (_sp > XB_SPIN_CAP) { atomicAdd(&(bar)[XB_TMO], 1u); break; } } } } while (0)
; __device__ __forceinline__ void xcd_barrier(const XcdBarrier& b) {
;     asm volatile("s_waitcnt vmcnt(0)" ::: "memory");
;     __syncthreads();
;     if (threadIdx.x == 0) {
;         unsigned* bar = b.bar;
;         __builtin_amdgcn_s_waitcnt(0);
;         unsigned nloc = b.st[0], nx = b.st[1];
;         if (nloc == 0u) { xcd_barrier_complete(bar, b.x, nloc, nx); b.st[0] = nloc; b.st[1] = nx; }
;         const unsigned old = xb_add(&bar[XB_XSUB(b.x)], 1u);
;         const unsigned gen = old / nloc;
;         if (old + 1u == (gen + 1u) * nloc) {
;             __builtin_amdgcn_fence(__ATOMIC_RELEASE, "agent");
;             asm volatile("s_waitcnt vmcnt(0)" ::: "memory");
;             const unsigned og = xb_add(&bar[XB_TOP], 1u);
;             const unsigned tg = og / nx;
;             if (og + 1u == (tg + 1u) * nx) xb_add(&bar[XB_TOPGEN], 1u);
;             else XB_SPIN(xb_ld(&bar[XB_TOPGEN]) == tg, bar);
;             __builtin_amdgcn_fence(__ATOMIC_ACQUIRE, "agent");
;             xb_add(&bar[XB_XGEN(b.x)], 1u);
;             asm volatile("s_waitcnt vmcnt(0)" ::: "memory");
.LBB0_963:
	s_waitcnt vmcnt(0) lgkmcnt(0)
	s_barrier
	v_readfirstlane_b32 s98, v222
	s_nop 3
	s_cmp_lg_u32 s98, 0
	s_cbranch_scc1 .Lsm7_done
	v_mov_b32_e32 v0, 0x23fc0
	ds_read_b64 v[2:3], v0
	v_readlane_b32 s99, v252, 3
	s_add_u32 s100, s58, 0x507000
	s_addc_u32 s101, s59, 0
	s_lshl_b32 s99, s99, 8
	v_mov_b32_e32 v0, s99
	v_mov_b32_e32 v1, 1
	s_mov_b64 exec, 1
	s_nop 1
	global_atomic_add v4, v0, v1, s[100:101] sc0
	s_waitcnt vmcnt(0) lgkmcnt(0)
	v_readfirstlane_b32 s99, v4
	v_readfirstlane_b32 vcc_lo, v2
	v_readfirstlane_b32 vcc_hi, v3
	s_add_u32 s100, s58, 0x500080
	s_addc_u32 s101, s59, 0
	v_mov_b32_e32 v0, 0
	s_add_u32 s99, s99, 1
	s_mul_i32 s98, vcc_lo, 6
	s_cmp_lg_u32 s99, s98
	s_cbranch_scc1 .Lsm7_nl
	buffer_wbl2 sc1
	s_waitcnt vmcnt(0)
	buffer_inv sc1
	s_waitcnt vmcnt(0)
	global_atomic_add v0, v1, s[100:101]
	s_branch .Lsm7_ld

; __device__ __forceinline__ unsigned xb_ld(unsigned* p)              { return __hip_atomic_load(p, __ATOMIC_RELAXED, __HIP_MEMORY_SCOPE_AGENT); }
; __device__ __forceinline__ unsigned xb_add(unsigned* p, unsigned v) { return __hip_atomic_fetch_add(p, v, __ATOMIC_RELAXED, __HIP_MEMORY_SCOPE_AGENT); }
; #define XB_SPIN(cond, bar) do { unsigned _sp = 0; while (cond) { __builtin_amdgcn_s_sleep(1); \
;     if ((++_sp & 255u) == 0u) { if (xb_ld(&(bar)[XB_TMO])) break; if (_sp > XB_SPIN_CAP) { atomicAdd(&(bar)[XB_TMO], 1u); break; } } } } while (0)
; __device__ __forceinline__ void xcd_barrier(const XcdBarrier& b) {
;     ...
;             const unsigned og = xb_add(&bar[XB_TOP], 1u);
;             const unsigned tg = og / nx;
;             if (og + 1u == (tg + 1u) * nx) xb_add(&bar[XB_TOPGEN], 1u);
;             else XB_SPIN(xb_ld(&bar[XB_TOPGEN]) == tg, bar);
.Lsm7_ld:
	s_mul_i32 s98, vcc_hi, 6
	s_mov_b32 s99, 0

; __device__ __forceinline__ unsigned xb_ld(unsigned* p)              { return __hip_atomic_load(p, __ATOMIC_RELAXED, __HIP_MEMORY_SCOPE_AGENT); }
; __device__ __forceinline__ unsigned xb_add(unsigned* p, unsigned v) { return __hip_atomic_fetch_add(p, v, __ATOMIC_RELAXED, __HIP_MEMORY_SCOPE_AGENT); }
; #define XB_SPIN(cond, bar) do { unsigned _sp = 0; while (cond) { __builtin_amdgcn_s_sleep(1); \
;     if ((++_sp & 255u) == 0u) { if (xb_ld(&(bar)[XB_TMO])) break; if (_sp > XB_SPIN_CAP) { atomicAdd(&(bar)[XB_TMO], 1u); break; } } } } while (0)
; __device__ __forceinline__ void xcd_barrier(const XcdBarrier& b) {
;     asm volatile("s_waitcnt vmcnt(0)" ::: "memory");
;     __syncthreads();
;     if (threadIdx.x == 0) {
;         unsigned* bar = b.bar;
;         __builtin_amdgcn_s_waitcnt(0);
;         unsigned nloc = b.st[0], nx = b.st[1];
;         if (nloc == 0u) { xcd_barrier_complete(bar, b.x, nloc, nx); b.st[0] = nloc; b.st[1] = nx; }
;         const unsigned old = xb_add(&bar[XB_XSUB(b.x)], 1u);
;         const unsigned gen = old / nloc;
;         if (old + 1u == (gen + 1u) * nloc) {
;             __builtin_amdgcn_fence(__ATOMIC_RELEASE, "agent");
;             asm volatile("s_waitcnt vmcnt(0)" ::: "memory");
;             const unsigned og = xb_add(&bar[XB_TOP], 1u);
;             const unsigned tg = og / nx;
;             if (og + 1u == (tg + 1u) * nx) xb_add(&bar[XB_TOPGEN], 1u);
;             else XB_SPIN(xb_ld(&bar[XB_TOPGEN]) == tg, bar);
;             __builtin_amdgcn_fence(__ATOMIC_ACQUIRE, "agent");
;             xb_add(&bar[XB_XGEN(b.x)], 1u);
;             asm volatile("s_waitcnt vmcnt(0)" ::: "memory");
.LBB0_1035:
	s_waitcnt vmcnt(0) lgkmcnt(0)
	s_barrier
	v_readfirstlane_b32 s98, v222
	s_nop 3
	s_cmp_lg_u32 s98, 0
	s_cbranch_scc1 .Lsm8_done
	v_mov_b32_e32 v0, 0x23fc0
	ds_read_b64 v[2:3], v0
	v_readlane_b32 s99, v252, 3
	s_add_u32 s100, s58, 0x507000
	s_addc_u32 s101, s59, 0
	s_lshl_b32 s99, s99, 8
	v_mov_b32_e32 v0, s99
	v_mov_b32_e32 v1, 1
	s_mov_b64 exec, 1
	s_nop 1
	global_atomic_add v4, v0, v1, s[100:101] sc0
	s_waitcnt vmcnt(0) lgkmcnt(0)
	v_readfirstlane_b32 s99, v4
	v_readfirstlane_b32 vcc_lo, v2
	v_readfirstlane_b32 vcc_hi, v3
	s_add_u32 s100, s58, 0x500080
	s_addc_u32 s101, s59, 0
	v_mov_b32_e32 v0, 0
	s_add_u32 s99, s99, 1
	s_mul_i32 s98, vcc_lo, 7
	s_cmp_lg_u32 s99, s98
	s_cbranch_scc1 .Lsm8_nl
	buffer_wbl2 sc1
	s_waitcnt vmcnt(0)
	buffer_inv sc1
	s_waitcnt vmcnt(0)
	global_atomic_add v0, v1, s[100:101]
	s_branch .Lsm8_ld

; __device__ __forceinline__ unsigned xb_ld(unsigned* p)              { return __hip_atomic_load(p, __ATOMIC_RELAXED, __HIP_MEMORY_SCOPE_AGENT); }
; __device__ __forceinline__ unsigned xb_add(unsigned* p, unsigned v) { return __hip_atomic_fetch_add(p, v, __ATOMIC_RELAXED, __HIP_MEMORY_SCOPE_AGENT); }
; #define XB_SPIN(cond, bar) do { unsigned _sp = 0; while (cond) { __builtin_amdgcn_s_sleep(1); \
;     if ((++_sp & 255u) == 0u) { if (xb_ld(&(bar)[XB_TMO])) break; if (_sp > XB_SPIN_CAP) { atomicAdd(&(bar)[XB_TMO], 1u); break; } } } } while (0)
; __device__ __forceinline__ void xcd_barrier(const XcdBarrier& b) {
;     ...
;             const unsigned og = xb_add(&bar[XB_TOP], 1u);
;             const unsigned tg = og / nx;
;             if (og + 1u == (tg + 1u) * nx) xb_add(&bar[XB_TOPGEN], 1u);
;             else XB_SPIN(xb_ld(&bar[XB_TOPGEN]) == tg, bar);
.Lsm8_ld:
	s_mul_i32 s98, vcc_hi, 7
	s_mov_b32 s99, 0
